# mixer queue: thread 0 pre-claims the next queue index while the current item runs (not across scan units)
# baseline (speedup 1.0000x reference)
.LBB0_682:
	s_cmp_gt_i32 s86, 5
	s_cselect_b64 s[0:1], -1, 0
	s_cmp_lt_i32 s87, 6
	s_cselect_b64 s[2:3], -1, 0
	v_writelane_b32 v254, s94, 2
	s_or_b64 s[0:1], s[0:1], s[2:3]
	s_and_b64 vcc, exec, s[0:1]
	v_writelane_b32 v254, s95, 3
	v_writelane_b32 v254, s96, 4
	v_writelane_b32 v254, s97, 5
	s_cbranch_vccnz .LBB0_1279
	s_add_u32 s36, s94, 0x118
	s_addc_u32 s37, s95, 0
	s_add_i32 s0, 0, 0x20180
	v_writelane_b32 v254, s0, 6
	v_mov_b32_e32 v207, s0
	s_add_i32 s0, 0, 0x20184
	v_writelane_b32 v254, s0, 7
	s_mov_b32 s59, 0
	v_mov_b32_e32 v206, 0x8000
	s_mov_b32 s33, 0x25801000
	s_mov_b32 s56, 0x25802000
	s_mov_b32 s57, 0x25803000
	s_waitcnt vmcnt(0)
	v_mov_b32_e32 v1, 0
	s_mov_b32 s38, 0xf800000
	v_mov_b32_e32 v208, 0x260
	s_mov_b64 s[60:61], 0x44c00000
	s_mov_b64 s[40:41], 0x44c00100
	s_mov_b64 s[42:43], 0x44c00200
	s_mov_b64 s[66:67], 0x44c00300
	s_mov_b64 s[68:69], 0x44c00400
	s_mov_b64 s[70:71], 0x44c00500
	s_mov_b64 s[72:73], 0x3000
	s_mov_b64 s[74:75], 0x10000
	s_mov_b64 s[76:77], 0x18000
	s_mov_b64 s[78:79], 0x39000
	v_mov_b32_e32 v209, 0x20000
	v_mov_b32_e32 v210, 1
	v_mov_b32_e32 v255, -1
	s_movk_i32 s39, 0x1000
	v_mov_b32_e32 v211, 0x10000
	v_mov_b32_e32 v212, 0xe000
	v_mov_b32_e32 v213, 0xc00000
	v_mov_b32_e32 v214, 0xffff8e00
	v_mov_b32_e32 v215, 0xff800000
	v_bfrev_b32_e32 v216, 0.5
	s_movk_i32 s89, 0xbf
	s_mov_b64 s[84:85], 0x100
	s_mov_b64 s[86:87], 0x1000
	s_mov_b64 s[44:45], 0x400
	v_writelane_b32 v254, s36, 9
	s_nop 1
	v_writelane_b32 v254, s37, 10
	s_branch .LBB0_687

.LBB0_687:
	v_mbcnt_lo_u32_b32 v204, -1, 0
	v_mbcnt_hi_u32_b32 v204, -1, v204
	s_load_dword s1, s[36:37], 0x0
	s_mov_b32 s28, s97
	s_mov_b32 s0, s96
	s_mov_b32 s12, s59
	s_waitcnt lgkmcnt(0)
	s_mov_b32 s65, s1
	s_load_dwordx2 s[90:91], s[94:95], 0x108
	s_waitcnt lgkmcnt(0)
	s_nop 0
	v_lshl_add_u32 v0, s28, 6, v204
	v_cmp_eq_u32_e64 s[0:1], 0, v0
	s_mov_b64 s[4:5], exec
	s_nop 0
	v_writelane_b32 v254, s0, 11
	s_nop 1
	v_writelane_b32 v254, s1, 12
	s_and_b64 s[0:1], s[4:5], s[0:1]
	s_mov_b64 exec, s[0:1]
	s_cbranch_execz .LBB0_691
	s_mov_b64 s[8:9], exec
	s_waitcnt vmcnt(0)
	v_mbcnt_lo_u32_b32 v2, s8, 0
	v_mbcnt_hi_u32_b32 v2, s9, v2
	v_cmp_eq_u32_e32 vcc, 0, v2
	s_and_saveexec_b64 s[6:7], vcc
	s_cbranch_execz .LBB0_690
	v_readfirstlane_b32 s0, v255
	s_cmp_lg_u32 s0, -1
	s_cbranch_scc1 .Lqp0_have
	v_mov_b32_e32 v3, 1
	s_nop 0
	global_atomic_add v3, v206, v3, s[90:91] sc0
	s_waitcnt vmcnt(0)
	v_readfirstlane_b32 s0, v3
.Lqp0_have:
	v_mov_b32_e32 v3, s0
	v_mov_b32_e32 v255, -1
	s_sub_u32 s0, s0, 0x100
	s_cmp_lt_u32 s0, 64
	s_cbranch_scc1 .LBB0_690
	v_mov_b32_e32 v255, 1
	s_nop 0
	global_atomic_add v255, v206, v255, s[90:91] sc0
.LBB0_690:
	s_or_b64 exec, exec, s[6:7]
	s_nop 0
	v_readfirstlane_b32 s0, v3
	s_nop 1
	v_add_u32_e32 v2, s0, v2
	v_readlane_b32 s0, v254, 6
	s_nop 1
	v_mov_b32_e32 v3, s0
	ds_write_b32 v3, v2
.LBB0_691:
	s_or_b64 exec, exec, s[4:5]
	s_waitcnt lgkmcnt(0)
	s_barrier
	s_cmp_eq_u32 s28, 0
	s_cbranch_scc1 .Lqp0_nw
	s_waitcnt vmcnt(0)
.Lqp0_nw:
	ds_read_b32 v2, v207
	s_movk_i32 s0, 0xdff
	s_mov_b64 s[4:5], -1
	s_waitcnt lgkmcnt(0)
	s_barrier
	v_cmp_lt_i32_e32 vcc, s0, v2
	v_readfirstlane_b32 s58, v2
	s_cbranch_vccnz .LBB0_686
	s_cmpk_lt_u32 s58, 2368
	s_cbranch_scc1 .Lq0_p0
	s_cmpk_ge_u32 s58, 3072
	s_cbranch_scc1 .Lq0_p0
	s_cmpk_ge_u32 s58, 2816
	s_cbranch_scc1 .Lq0_pa
	s_addk_i32 s58, 256
	s_branch .Lq0_p0

.LBB0_2303:
	s_cmp_gt_i32 s86, 20
	s_cselect_b64 s[0:1], -1, 0
	s_cmp_lt_i32 s87, 21
	s_cselect_b64 s[2:3], -1, 0
	s_or_b64 s[0:1], s[0:1], s[2:3]
	s_and_b64 vcc, exec, s[0:1]
	s_cbranch_vccnz .LBB0_2900
	s_add_u32 s36, s94, 0x118
	s_addc_u32 s37, s95, 0
	s_add_i32 s65, 0, 0x20180
	v_writelane_b32 v254, s36, 7
	s_mov_b32 s59, 0
	v_mov_b32_e32 v206, 0x8000
	v_mov_b32_e32 v207, s65
	s_movk_i32 s38, 0x4000
	s_movk_i32 s39, 0x600
	s_movk_i32 s40, 0x3000
	s_movk_i32 s41, 0x7200
	s_mov_b32 s33, 0x25801000
	s_mov_b32 s56, 0x25802000
	s_mov_b32 s57, 0x25803000
	s_waitcnt vmcnt(0)
	v_mov_b32_e32 v1, 0
	s_mov_b32 s42, 0xf800000
	v_mov_b32_e32 v208, 0x260
	s_mov_b64 s[60:61], 0x44c00000
	s_mov_b64 s[44:45], 0x44c00100
	s_mov_b64 s[46:47], 0x44c00200
	s_mov_b64 s[66:67], 0x44c00300
	s_mov_b64 s[68:69], 0x44c00400
	s_mov_b64 s[70:71], 0x44c00500
	s_mov_b64 s[72:73], 0x3000
	s_mov_b64 s[74:75], 0x10000
	s_mov_b64 s[76:77], 0x18000
	s_mov_b64 s[78:79], 0x39000
	v_mov_b32_e32 v209, 0x21000
	v_mov_b32_e32 v210, 1
	v_mov_b32_e32 v255, -1
	v_mov_b32_e32 v211, 0xc000
	s_add_i32 s43, 0, 0x20184
	s_mov_b32 s49, 0x41000000
	s_movk_i32 s50, 0x1000
	s_mov_b32 s52, 0x62d00000
	v_mov_b32_e32 v212, 0x12000
	v_mov_b32_e32 v213, 0xe000
	v_mov_b32_e32 v214, 0xc00000
	v_mov_b32_e32 v215, 0xffff8e00
	v_mov_b32_e32 v216, 0xff800000
	v_bfrev_b32_e32 v217, 0.5
	s_movk_i32 s89, 0xbf
	s_mov_b64 s[84:85], 0x100
	s_mov_b64 s[86:87], 0x1000
	s_mov_b64 s[54:55], 0x400
	v_writelane_b32 v254, s37, 8
	v_writelane_b32 v254, s43, 9
	s_branch .LBB0_2308

.LBB0_2308:
	v_mbcnt_lo_u32_b32 v204, -1, 0
	v_mbcnt_hi_u32_b32 v204, -1, v204
	s_load_dword s51, s[36:37], 0x0
	s_mov_b32 s28, s97
	s_mov_b32 s0, s96
	s_mov_b32 s12, 1
	s_waitcnt lgkmcnt(0)
	s_mov_b32 s1, s51
	s_load_dwordx2 s[90:91], s[94:95], 0x108
	s_waitcnt lgkmcnt(0)
	s_nop 0
	v_lshl_add_u32 v0, s28, 6, v204
	v_cmp_eq_u32_e64 s[0:1], 0, v0
	s_mov_b64 s[4:5], exec
	s_nop 0
	v_writelane_b32 v254, s0, 11
	s_nop 1
	v_writelane_b32 v254, s1, 12
	s_and_b64 s[0:1], s[4:5], s[0:1]
	s_mov_b64 exec, s[0:1]
	s_cbranch_execz .LBB0_2312
	s_mov_b64 s[8:9], exec
	s_waitcnt vmcnt(0)
	v_mbcnt_lo_u32_b32 v2, s8, 0
	v_mbcnt_hi_u32_b32 v2, s9, v2
	v_cmp_eq_u32_e32 vcc, 0, v2
	s_and_saveexec_b64 s[6:7], vcc
	s_cbranch_execz .LBB0_2311
	v_readfirstlane_b32 s0, v255
	s_cmp_lg_u32 s0, -1
	s_cbranch_scc1 .Lqp1_have
	v_mov_b32_e32 v3, 1
	s_nop 0
	global_atomic_add v3, v206, v3, s[90:91] offset:256 sc0
	s_waitcnt vmcnt(0)
	v_readfirstlane_b32 s0, v3
.Lqp1_have:
	v_mov_b32_e32 v3, s0
	v_mov_b32_e32 v255, -1
	s_sub_u32 s0, s0, 0x100
	s_cmp_lt_u32 s0, 64
	s_cbranch_scc1 .LBB0_2311
	v_mov_b32_e32 v255, 1
	s_nop 0
	global_atomic_add v255, v206, v255, s[90:91] offset:256 sc0
.LBB0_2311:
	s_or_b64 exec, exec, s[6:7]
	s_nop 0
	v_readfirstlane_b32 s0, v3
	v_mov_b32_e32 v3, s65
	s_nop 0
	v_add_u32_e32 v2, s0, v2
	ds_write_b32 v3, v2

	.amdhsa_kernel _Z6mk_fwd4Args
		.amdhsa_group_segment_fixed_size 0
		.amdhsa_private_segment_fixed_size 0
		.amdhsa_kernarg_size 536
		.amdhsa_user_sgpr_count 2
		.amdhsa_user_sgpr_dispatch_ptr 0
		.amdhsa_user_sgpr_queue_ptr 0
		.amdhsa_user_sgpr_kernarg_segment_ptr 1
		.amdhsa_user_sgpr_dispatch_id 0
		.amdhsa_user_sgpr_kernarg_preload_length 0
		.amdhsa_user_sgpr_kernarg_preload_offset 0
		.amdhsa_user_sgpr_private_segment_size 0
		.amdhsa_uses_dynamic_stack 0
		.amdhsa_enable_private_segment 0
		.amdhsa_system_sgpr_workgroup_id_x 1
		.amdhsa_system_sgpr_workgroup_id_y 0
		.amdhsa_system_sgpr_workgroup_id_z 0
		.amdhsa_system_sgpr_workgroup_info 0
		.amdhsa_system_vgpr_workitem_id 0
		.amdhsa_next_free_vgpr 256
		.amdhsa_next_free_sgpr 98
		.amdhsa_accum_offset 256
		.amdhsa_reserve_vcc 1
		.amdhsa_float_round_mode_32 0
		.amdhsa_float_round_mode_16_64 0
		.amdhsa_float_denorm_mode_32 3
		.amdhsa_float_denorm_mode_16_64 3
		.amdhsa_dx10_clamp 1
		.amdhsa_ieee_mode 1
		.amdhsa_fp16_overflow 0
		.amdhsa_tg_split 0
		.amdhsa_exception_fp_ieee_invalid_op 0
		.amdhsa_exception_fp_denorm_src 0
		.amdhsa_exception_fp_ieee_div_zero 0
		.amdhsa_exception_fp_ieee_overflow 0
		.amdhsa_exception_fp_ieee_underflow 0
		.amdhsa_exception_fp_ieee_inexact 0
		.amdhsa_exception_int_div_zero 0
	.end_amdhsa_kernel

amdhsa.kernels:
  - .agpr_count:     0
    .args:
      - .offset:         0
        .size:           280
        .value_kind:     by_value
      - .offset:         280
        .size:           4
        .value_kind:     hidden_block_count_x
      - .offset:         284
        .size:           4
        .value_kind:     hidden_block_count_y
      - .offset:         288
        .size:           4
        .value_kind:     hidden_block_count_z
      - .offset:         292
        .size:           2
        .value_kind:     hidden_group_size_x
      - .offset:         294
        .size:           2
        .value_kind:     hidden_group_size_y
      - .offset:         296
        .size:           2
        .value_kind:     hidden_group_size_z
      - .offset:         298
        .size:           2
        .value_kind:     hidden_remainder_x
      - .offset:         300
        .size:           2
        .value_kind:     hidden_remainder_y
      - .offset:         302
        .size:           2
        .value_kind:     hidden_remainder_z
      - .offset:         320
        .size:           8
        .value_kind:     hidden_global_offset_x
      - .offset:         328
        .size:           8
        .value_kind:     hidden_global_offset_y
      - .offset:         336
        .size:           8
        .value_kind:     hidden_global_offset_z
      - .offset:         344
        .size:           2
        .value_kind:     hidden_grid_dims
      - .offset:         400
        .size:           4
        .value_kind:     hidden_dynamic_lds_size
    .group_segment_fixed_size: 0
    .kernarg_segment_align: 8
    .kernarg_segment_size: 536
    .language:       OpenCL C
    .language_version:
      - 2
      - 0
    .max_flat_workgroup_size: 512
    .name:           _Z6mk_fwd4Args
    .private_segment_fixed_size: 0
    .sgpr_count:     104
    .sgpr_spill_count: 20
    .symbol:         _Z6mk_fwd4Args.kd
    .uniform_work_group_size: 1
    .uses_dynamic_stack: false
    .vgpr_count:     256
    .vgpr_spill_count: 0
    .wavefront_size: 64
